# v36 + one static s_setprio 1 for waves 4-7 (younger half) during the attention phase
# speedup vs baseline: 1.0108x; 1.0049x over previous
; #define LAS __attribute__((address_space(3)))
; DI int obid() { int t = blockIdx.x; asm volatile("" : "+s"(t)); return t; }
; DI int ogrid() { int t = gridDim.x; asm volatile("" : "+s"(t)); return t; }
; DI int otid() { int t = threadIdx.x; asm volatile("" : "+v"(t)); return t; }
; DI unsigned char* opq(unsigned char* p) { asm volatile("" : "+s"(p)); return p; }
; #define P (kparams())
; DI void attn_unit(LAS unsigned char* lds, const bf16_t* __restrict__ Q, const bf16_t* __restrict__ Kg, const bf16_t* __restrict__ VT, bf16_t* __restrict__ MIX, int b, int h, int c0, int nq, int desc) {
;   const int tid = otid(), wave = tid >> 6, lane = tid & 63, r31 = lane & 31, hh = lane >> 5;
;   const bool active = (wave >> 1) < nq; const int cq = c0 + (wave >> 1); const int nt = c0 + nq;
;   const size_t qrow = (size_t)b * LP + 64 * c0 + (active ? 32 * wave + r31 : 0);
;   bf16x8 qf[12];
;   { const bf16_t* qp = Q + qrow * 768 + h * 192 + 8 * hh;
; #pragma unroll
;     for (int s = 0; s < 12; ++s) qf[s] = *(const bf16x8*)(qp + 16 * s); }
;   f32x16 O[4];
; #pragma unroll
;   for (int d = 0; d < 4; ++d)
; #pragma unroll
;     for (int i = 0; i < 16; ++i) O[d][i] = 0.f;
;   float mrun = NEG_INF, lrun = 0.f;
;   const bf16_t* kbase = Kg + (size_t)b * LP * 768 + h * 192;
;   const bf16_t* vbase = VT + (size_t)(b * 4 + h) * 128 * LP;
; DI void phase_attn(KP P, LAS unsigned char* lds) {
;   const bf16_t* Q = (const bf16_t*)(opq(P->ws) + OFF_BIG + B_QP); const bf16_t* Kg = (const bf16_t*)(opq(P->ws) + OFF_BIG + B_KK); const bf16_t* VT = (const bf16_t*)(opq(P->ws) + OFF_BIG + B_VT);
;   bf16_t* MIX = (bf16_t*)(opq(P->ws) + OFF_U);
;   for (int j = obid(); j < 256; j += ogrid()) {
;     const int bh = j & 7, pi = j >> 3; const int b = bh >> 2, h = bh & 3;
;     attn_unit(lds, Q, Kg, VT, MIX, b, h, 4 * (64 - pi) - 3, 4, 0);
.LBB0_526:
	s_or_b64 exec, exec, s[58:59]
	s_mov_b64 s[4:5], s[88:89]
	s_waitcnt lgkmcnt(0)
	s_barrier
	s_load_dwordx2 s[4:5], s[4:5], 0x98
	s_mov_b32 s3, s2
	s_waitcnt lgkmcnt(0)
	s_mov_b64 s[8:9], s[4:5]
	s_mov_b64 s[6:7], s[4:5]
	s_mov_b64 s[10:11], s[4:5]
	s_cmpk_gt_i32 s3, 0xff
	s_cbranch_scc1 .LBB0_627
	s_add_u32 s8, s8, 0x12712000
	s_addc_u32 s9, s9, 0
	s_add_u32 s33, s6, 0x15772000
	s_addc_u32 s36, s7, 0
	s_add_u32 s37, s10, 0x187d2000
	s_addc_u32 s42, s11, 0
	s_add_u32 s10, s4, 0x210a000
	s_addc_u32 s11, s5, 0
	s_movk_i32 s43, 0x4040
	v_readfirstlane_b32 s99, v224
	s_mov_b32 s99, 0
	s_mov_b32 s13, 0
	s_movk_i32 s58, 0xffe0
	s_movk_i32 s59, 0x600
	v_mov_b64_e32 v[216:217], s[8:9]
	v_mov_b32_e32 v1, 0
	s_movk_i32 s60, 0x300
	s_movk_i32 s61, 0x90
	s_movk_i32 s62, 0x190
	s_lshr_b32 s99, s99, 8
	s_cmp_lg_u32 s99, 0
	s_cbranch_scc0 .Lprio_skip_1
	s_setprio 1

; #define LAS __attribute__((address_space(3)))
; DI int obid() { int t = blockIdx.x; asm volatile("" : "+s"(t)); return t; }
; DI int ogrid() { int t = gridDim.x; asm volatile("" : "+s"(t)); return t; }
; DI int otid() { int t = threadIdx.x; asm volatile("" : "+v"(t)); return t; }
; DI unsigned char* opq(unsigned char* p) { asm volatile("" : "+s"(p)); return p; }
; #define P (kparams())
; DI void attn_unit(LAS unsigned char* lds, const bf16_t* __restrict__ Q, const bf16_t* __restrict__ Kg, const bf16_t* __restrict__ VT, bf16_t* __restrict__ MIX, int b, int h, int c0, int nq, int desc) {
;   const int tid = otid(), wave = tid >> 6, lane = tid & 63, r31 = lane & 31, hh = lane >> 5;
;   const bool active = (wave >> 1) < nq; const int cq = c0 + (wave >> 1); const int nt = c0 + nq;
;   const size_t qrow = (size_t)b * LP + 64 * c0 + (active ? 32 * wave + r31 : 0);
;   bf16x8 qf[12];
;   { const bf16_t* qp = Q + qrow * 768 + h * 192 + 8 * hh;
; #pragma unroll
;     for (int s = 0; s < 12; ++s) qf[s] = *(const bf16x8*)(qp + 16 * s); }
;   f32x16 O[4];
; #pragma unroll
;   for (int d = 0; d < 4; ++d)
; #pragma unroll
;     for (int i = 0; i < 16; ++i) O[d][i] = 0.f;
;   float mrun = NEG_INF, lrun = 0.f;
;   const bf16_t* kbase = Kg + (size_t)b * LP * 768 + h * 192;
;   const bf16_t* vbase = VT + (size_t)(b * 4 + h) * 128 * LP;
; DI void phase_attn(KP P, LAS unsigned char* lds) {
;   const bf16_t* Q = (const bf16_t*)(opq(P->ws) + OFF_BIG + B_QP); const bf16_t* Kg = (const bf16_t*)(opq(P->ws) + OFF_BIG + B_KK); const bf16_t* VT = (const bf16_t*)(opq(P->ws) + OFF_BIG + B_VT);
;   bf16_t* MIX = (bf16_t*)(opq(P->ws) + OFF_U);
;   for (int j = obid(); j < 256; j += ogrid()) {
;     const int bh = j & 7, pi = j >> 3; const int b = bh >> 2, h = bh & 3;
;     attn_unit(lds, Q, Kg, VT, MIX, b, h, 4 * (64 - pi) - 3, 4, 0);
.LBB0_2537:
	s_or_b64 exec, exec, s[58:59]
	s_mov_b64 s[4:5], s[88:89]
	s_waitcnt lgkmcnt(0)
	s_barrier
	s_load_dwordx2 s[4:5], s[4:5], 0x98
	v_readlane_b32 s3, v254, 12
	s_waitcnt lgkmcnt(0)
	s_mov_b64 s[8:9], s[4:5]
	s_mov_b64 s[6:7], s[4:5]
	s_mov_b64 s[10:11], s[4:5]
	s_cmpk_gt_i32 s3, 0xff
	s_cbranch_scc1 .LBB0_2638
	s_add_u32 s8, s8, 0x12712000
	s_addc_u32 s9, s9, 0
	s_add_u32 s33, s6, 0x15772000
	s_addc_u32 s36, s7, 0
	s_add_u32 s37, s10, 0x187d2000
	s_addc_u32 s42, s11, 0
	s_add_u32 s10, s4, 0x210a000
	s_addc_u32 s11, s5, 0
	s_movk_i32 s43, 0x4040
	v_readfirstlane_b32 s99, v224
	s_mov_b32 s99, 0
	s_mov_b32 s13, 0
	s_movk_i32 s58, 0xffe0
	s_movk_i32 s59, 0x600
	v_mov_b64_e32 v[216:217], s[8:9]
	v_mov_b32_e32 v1, 0
	s_movk_i32 s60, 0x300
	s_movk_i32 s61, 0x90
	s_movk_i32 s62, 0x190
	s_lshr_b32 s99, s99, 8
	s_cmp_lg_u32 s99, 0
	s_cbranch_scc0 .Lprio_skip_4
	s_setprio 1
